# phase8 xq GEMM mainloop rewritten: 3-stage LDS-DMA (global_load_lds) pipeline, swizzled LDS, static LDS 80KB
# speedup vs baseline: 1.0031x; 1.0031x over previous
; DI bfr f2bf(float a) { return (bfr)(pack2(a, 0.f) & 0xffffu); }
; DI int crow(int reg, int h) { return (reg & 3) + 8 * (reg >> 2) + 4 * h; }
; template <int lda, class Epi>
; DI void gemm_tile(const bfr* __restrict__ A, const bfr* __restrict__ Bt, int NB, int K, int m0, int n0, char* smem, Epi epi) {
;     ...
; #pragma unroll
;   for (int i = 0; i < 2; ++i)
; #pragma unroll
;     for (int j = 0; j < 4; ++j)
; #pragma unroll
;       for (int q = 0; q < 16; ++q) {
;         int row = m0 + wr * 64 + i * 32 + crow(q, hl);
;         int col = n0 + wc * 128 + j * 32 + r;
;         epi(row, col, acc[i][j][q]);
;       }
; DI void phase_gemm_bf16out(const Params& p, const bfr* A, const bfr* Wt, bfr* C, int N, const float* ss, char* smem) {
;     ...
;   for (int t0 = blockIdx.x; t0 < 128 * ntn; t0 += gridDim.x) {
;     const int t = ((gridDim.x & 7) == 0) ? xcd_tile(t0, ntn) : t0;
;     int mt = t / ntn, nt = t % ntn;
;     gemm_tile<1024>(A, Wt, N, 1024, mt * 128, nt * 256, smem,
;               [=](int row, int col, float v) {
;                 float inv = rsqrtf(ss[row] * (1.0f / 1024.0f) + EPSF);
;                 C[(size_t)row * N + col] = f2bf(v * inv);
;               });
.LBB0_922:
	s_nop 0
	s_nop 0
	s_nop 0
	s_nop 0
	s_nop 0
	s_nop 0
	s_nop 0
	s_nop 0
	s_nop 0
	s_nop 0
	s_nop 0
	s_nop 0
	s_nop 0
	s_nop 0
	s_nop 0
	s_nop 0
	s_nop 0
	s_nop 0
	s_nop 0
	s_nop 0
	s_nop 0
	s_nop 0
	s_nop 0
	s_waitcnt lgkmcnt(0)
	s_nop 0
	s_nop 0
	s_nop 0
	s_nop 0
	v_mov_b64_e32 v[204:205], s[18:19]
	s_add_i32 s28, s28, s34
	s_cmpk_lt_i32 s28, 0x200
	s_nop 0
	s_nop 0
	s_nop 0
	s_nop 0
	s_nop 0
	s_nop 0
	s_nop 0
	s_nop 0
	s_nop 0
	s_nop 0
	s_nop 0
	s_nop 0
	s_nop 0
	s_nop 0
	v_mov_b32_e32 v197, v196
	s_waitcnt lgkmcnt(0)
	s_nop 0
	s_nop 0
	v_ashrrev_i32_e32 v198, 1, v197
	v_and_b32_e32 v198, 0xffffffc0, v198
	s_nop 0
	v_lshrrev_b32_e32 v200, 3, v197
	v_add_u32_e32 v198, s30, v198
	v_and_or_b32 v200, v200, 4, v198
	v_ashrrev_i32_e32 v201, 31, v200
	v_lshl_add_u64 v[206:207], v[200:201], 2, s[8:9]
	global_load_dwordx4 v[226:229], v[206:207], off
	v_and_b32_e32 v198, 31, v197
	s_nop 0
	v_lshlrev_b32_e32 v197, 1, v197
	v_and_b32_e32 v197, 0x80, v197
	v_or3_b32 v202, v198, v197, s29
	v_or_b32_e32 v208, 1, v200
	v_or_b32_e32 v212, 2, v200
	v_ashrrev_i32_e32 v203, 31, v202
	v_ashrrev_i32_e32 v209, 31, v208
	s_nop 0
	global_load_dwordx4 v[218:221], v[206:207], off offset:32
	v_ashrrev_i32_e32 v213, 31, v212
	v_lshl_add_u64 v[202:203], v[202:203], 1, s[2:3]
	v_lshlrev_b64 v[208:209], 11, v[208:209]
	v_lshlrev_b64 v[222:223], 11, v[212:213]
	v_lshl_add_u64 v[212:213], v[202:203], 0, v[208:209]
	v_lshl_add_u64 v[208:209], v[202:203], 0, v[222:223]
	s_nop 0
	v_lshlrev_b64 v[210:211], 11, v[200:201]
	v_lshl_add_u64 v[210:211], v[202:203], 0, v[210:211]
	s_waitcnt vmcnt(1)
	v_fma_f32 v222, v226, s16, v204
	v_fma_f32 v223, v227, s16, v204
	s_nop 0
	v_mul_f32_e32 v197, 0x4b800000, v222
	v_cmp_gt_f32_e32 vcc, s27, v222
	v_mul_f32_e32 v198, 0x4b800000, v223
	v_cmp_gt_f32_e64 s[4:5], s27, v223
	v_cndmask_b32_e32 v197, v222, v197, vcc
	v_rsq_f32_e32 v197, v197
	v_cndmask_b32_e64 v198, v223, v198, s[4:5]
	s_nop 0
	v_fma_f32 v224, v228, s16, v204
	v_fma_f32 v225, v229, s16, v204
	v_rsq_f32_e32 v222, v198
	v_mul_f32_e32 v201, 0x4b800000, v224
	v_cmp_gt_f32_e64 s[6:7], s27, v224
	v_mul_f32_e32 v198, 0x45800000, v197
	v_mul_f32_e32 v223, 0x45800000, v222
	v_cndmask_b32_e64 v201, v224, v201, s[6:7]
	v_rsq_f32_e32 v201, v201
	v_cndmask_b32_e32 v198, v197, v198, vcc
	v_cndmask_b32_e64 v197, v222, v223, s[4:5]
	s_nop 0
	v_mul_f32_e32 v112, v112, v198
	v_mul_f32_e32 v113, v113, v197
	v_cvt_pk_bf16_f32 v112, v112, s0
	v_cvt_pk_bf16_f32 v113, v113, s0
	global_store_short v[210:211], v112, off
	global_store_short v[212:213], v113, off
	v_mul_f32_e32 v222, 0x45800000, v201
	s_nop 0
	v_cndmask_b32_e64 v201, v201, v222, s[6:7]
	v_mul_f32_e32 v222, 0x4b800000, v225
	v_cmp_gt_f32_e32 vcc, s27, v225
	v_mul_f32_e32 v114, v114, v201
	v_cvt_pk_bf16_f32 v114, v114, s0
	v_cndmask_b32_e32 v222, v225, v222, vcc
	v_rsq_f32_e32 v222, v222
	s_nop 0
	global_store_short v[208:209], v114, off
	v_or_b32_e32 v112, 3, v200
	v_mul_f32_e32 v114, 0x45800000, v222
	v_cndmask_b32_e32 v222, v222, v114, vcc
	v_ashrrev_i32_e32 v113, 31, v112
	v_mul_f32_e32 v114, v115, v222
	v_lshlrev_b64 v[112:113], 11, v[112:113]
	s_nop 0
	global_load_dwordx4 v[214:217], v[206:207], off offset:64
	v_cvt_pk_bf16_f32 v114, v114, s0
	v_lshl_add_u64 v[112:113], v[202:203], 0, v[112:113]
	global_store_short v[112:113], v114, off
	v_or_b32_e32 v114, 8, v200
	v_ashrrev_i32_e32 v115, 31, v114
	v_lshlrev_b64 v[114:115], 11, v[114:115]
	s_nop 0
	s_waitcnt vmcnt(5)
	v_fma_f32 v176, v218, s16, v204
	v_fma_f32 v177, v219, s16, v204
	v_lshl_add_u64 v[114:115], v[202:203], 0, v[114:115]
	v_mul_f32_e32 v178, 0x4b800000, v176
	v_cmp_gt_f32_e32 vcc, s27, v176
	s_nop 1
	v_cndmask_b32_e32 v176, v176, v178, vcc
	v_rsq_f32_e32 v176, v176
	s_nop 0
	v_or_b32_e32 v178, 9, v200
	v_ashrrev_i32_e32 v179, 31, v178
	v_mul_f32_e32 v188, 0x45800000, v176
	v_cndmask_b32_e32 v188, v176, v188, vcc
	v_mul_f32_e32 v176, 0x4b800000, v177
	v_cmp_gt_f32_e32 vcc, s27, v177
	v_mul_f32_e32 v116, v116, v188
	v_cvt_pk_bf16_f32 v116, v116, s0
	v_cndmask_b32_e32 v176, v177, v176, vcc
	v_rsq_f32_e32 v176, v176
	global_store_short v[114:115], v116, off
	s_nop 0
	v_or_b32_e32 v180, 11, v200
	v_mul_f32_e32 v116, 0x45800000, v176
	v_cndmask_b32_e32 v182, v176, v116, vcc
	v_mul_f32_e32 v116, v117, v182
	v_ashrrev_i32_e32 v181, 31, v180
	s_nop 0
	v_cvt_pk_bf16_f32 v172, v116, s0
	v_lshlrev_b64 v[116:117], 11, v[178:179]
	v_fma_f32 v178, v220, s16, v204
	v_fma_f32 v179, v221, s16, v204
	v_lshl_add_u64 v[116:117], v[202:203], 0, v[116:117]
	v_mul_f32_e32 v174, 0x4b800000, v178
	v_cmp_gt_f32_e32 vcc, s27, v178
	global_store_short v[116:117], v172, off
	s_nop 0
	v_cndmask_b32_e32 v174, v178, v174, vcc
	v_rsq_f32_e32 v174, v174
	v_or_b32_e32 v172, 10, v200
	v_ashrrev_i32_e32 v173, 31, v172
	v_lshlrev_b64 v[172:173], 11, v[172:173]
	v_mul_f32_e32 v175, 0x45800000, v174
	v_cndmask_b32_e32 v178, v174, v175, vcc
	global_load_dwordx4 v[174:177], v[206:207], off offset:96
	s_nop 0
	v_lshl_add_u64 v[172:173], v[202:203], 0, v[172:173]
	v_mul_f32_e32 v183, 0x4b800000, v179
	v_cmp_gt_f32_e32 vcc, s27, v179
	v_mul_f32_e32 v118, v118, v178
	v_cvt_pk_bf16_f32 v118, v118, s0
	v_cndmask_b32_e32 v179, v179, v183, vcc
	v_rsq_f32_e32 v179, v179
	s_nop 4
	v_mul_f32_e32 v80, v80, v198
	v_cvt_pk_bf16_f32 v80, v80, s0
	global_store_short v[210:211], v80, off offset:128
	v_mul_f32_e32 v80, v81, v197
	v_cvt_pk_bf16_f32 v80, v80, s0
	global_store_short v[212:213], v80, off offset:128
	v_mul_f32_e32 v80, v82, v201
	v_cvt_pk_bf16_f32 v80, v80, s0
	global_store_short v[208:209], v80, off offset:128
	v_mul_f32_e32 v80, v83, v222
	v_cvt_pk_bf16_f32 v80, v80, s0
	global_store_short v[112:113], v80, off offset:128
	v_mul_f32_e32 v80, v84, v188
	v_cvt_pk_bf16_f32 v80, v80, s0
	global_store_short v[114:115], v80, off offset:128
	v_mul_f32_e32 v80, v85, v182
	v_cvt_pk_bf16_f32 v80, v80, s0
	global_store_short v[116:117], v80, off offset:128
	v_mul_f32_e32 v80, v86, v178
	v_cvt_pk_bf16_f32 v80, v80, s0
	global_store_short v[172:173], v80, off offset:128
	global_load_dwordx4 v[80:83], v[206:207], off offset:128
	s_nop 0
	global_store_short v[172:173], v118, off
	v_mul_f32_e32 v118, 0x45800000, v179
	v_cndmask_b32_e32 v179, v179, v118, vcc
	v_mul_f32_e32 v118, v119, v179
	v_mul_f32_e32 v84, v87, v179
	v_cvt_pk_bf16_f32 v84, v84, s0
	s_nop 0
	s_nop 0
	v_cvt_pk_bf16_f32 v158, v118, s0
	v_lshlrev_b64 v[118:119], 11, v[180:181]
	v_lshl_add_u64 v[156:157], v[202:203], 0, v[118:119]
	v_or_b32_e32 v118, 16, v200
	v_ashrrev_i32_e32 v119, 31, v118
	v_lshlrev_b64 v[118:119], 11, v[118:119]
	global_store_short v[156:157], v158, off
	v_lshl_add_u64 v[158:159], v[202:203], 0, v[118:119]
	s_waitcnt vmcnt(14)
; DI bfr f2bf(float a) { return (bfr)(pack2(a, 0.f) & 0xffffu); }
; DI int crow(int reg, int h) { return (reg & 3) + 8 * (reg >> 2) + 4 * h; }
; template <int lda, class Epi>
; DI void gemm_tile(const bfr* __restrict__ A, const bfr* __restrict__ Bt, int NB, int K, int m0, int n0, char* smem, Epi epi) {
;     ...
; #pragma unroll
;   for (int i = 0; i < 2; ++i)
; #pragma unroll
;     for (int j = 0; j < 4; ++j)
; #pragma unroll
;       for (int q = 0; q < 16; ++q) {
;         int row = m0 + wr * 64 + i * 32 + crow(q, hl);
;         int col = n0 + wc * 128 + j * 32 + r;
;         epi(row, col, acc[i][j][q]);
;       }
; DI void phase_gemm_bf16out(const Params& p, const bfr* A, const bfr* Wt, bfr* C, int N, const float* ss, char* smem) {
;     ...
;   for (int t0 = blockIdx.x; t0 < 128 * ntn; t0 += gridDim.x) {
;     const int t = ((gridDim.x & 7) == 0) ? xcd_tile(t0, ntn) : t0;
;     int mt = t / ntn, nt = t % ntn;
;     gemm_tile<1024>(A, Wt, N, 1024, mt * 128, nt * 256, smem,
;               [=](int row, int col, float v) {
;                 float inv = rsqrtf(ss[row] * (1.0f / 1024.0f) + EPSF);
;                 C[(size_t)row * N + col] = f2bf(v * inv);
;               });
	v_pk_fma_f32 v[118:119], v[214:215], s[16:17], v[204:205] op_sel_hi:[1,0,0]
	s_nop 0
	v_mul_f32_e32 v164, 0x4b800000, v118
	v_cmp_gt_f32_e32 vcc, s27, v118
	v_mul_f32_e32 v64, v64, v198
	v_cvt_pk_bf16_f32 v64, v64, s0
	v_cndmask_b32_e32 v118, v118, v164, vcc
	v_rsq_f32_e32 v118, v118
	global_store_short v[210:211], v64, off offset:192
	v_mul_f32_e32 v64, v65, v197
	v_cvt_pk_bf16_f32 v64, v64, s0
	global_store_short v[212:213], v64, off offset:192
	v_mul_f32_e32 v64, v66, v201
	v_cvt_pk_bf16_f32 v64, v64, s0
	s_nop 0
	global_store_short v[208:209], v64, off offset:192
	v_mul_f32_e32 v64, v67, v222
	v_cvt_pk_bf16_f32 v64, v64, s0
	global_store_short v[112:113], v64, off offset:192
	v_mul_f32_e32 v64, v68, v188
	v_cvt_pk_bf16_f32 v64, v64, s0
	global_store_short v[114:115], v64, off offset:192
	s_nop 0
	v_mul_f32_e32 v152, 0x45800000, v118
	v_cndmask_b32_e32 v154, v118, v152, vcc
	v_mul_f32_e32 v118, v120, v154
	v_mul_f32_e32 v120, 0x4b800000, v119
	v_cmp_gt_f32_e32 vcc, s27, v119
	v_mul_f32_e32 v64, v69, v182
	v_cvt_pk_bf16_f32 v64, v64, s0
	s_nop 0
	v_cndmask_b32_e32 v119, v119, v120, vcc
	v_rsq_f32_e32 v119, v119
	global_store_short v[116:117], v64, off offset:192
	v_mul_f32_e32 v64, v70, v178
	v_cvt_pk_bf16_f32 v118, v118, s0
	v_cvt_pk_bf16_f32 v64, v64, s0
	global_store_short v[158:159], v118, off
	v_mul_f32_e32 v118, 0x45800000, v119
	v_pk_fma_f32 v[152:153], v[216:217], s[16:17], v[204:205] op_sel_hi:[1,0,0]
	global_store_short v[172:173], v64, off offset:192
	v_mul_f32_e32 v64, v71, v179
	global_load_dwordx4 v[68:71], v[206:207], off offset:160
	v_cndmask_b32_e32 v155, v119, v118, vcc
	v_mul_f32_e32 v160, 0x4b800000, v152
	v_cmp_gt_f32_e32 vcc, s27, v152
	s_nop 0
	v_or_b32_e32 v164, 17, v200
	v_cndmask_b32_e32 v140, v152, v160, vcc
	v_rsq_f32_e32 v142, v140
	v_ashrrev_i32_e32 v165, 31, v164
	v_mul_f32_e32 v118, v121, v155
	v_cvt_pk_bf16_f32 v120, v118, s0
	v_mul_f32_e32 v143, 0x45800000, v142
	v_lshlrev_b64 v[118:119], 11, v[164:165]
	v_cndmask_b32_e32 v142, v142, v143, vcc
	s_nop 0
	v_mul_f32_e32 v136, 0x4b800000, v153
	v_cmp_gt_f32_e32 vcc, s27, v153
	v_lshl_add_u64 v[118:119], v[202:203], 0, v[118:119]
	global_store_short v[118:119], v120, off
	v_cndmask_b32_e32 v136, v153, v136, vcc
	v_or_b32_e32 v120, 18, v200
	v_rsq_f32_e32 v136, v136
	v_ashrrev_i32_e32 v121, 31, v120
	v_lshlrev_b64 v[120:121], 11, v[120:121]
	v_mul_f32_e32 v122, v122, v142
	v_lshl_add_u64 v[120:121], v[202:203], 0, v[120:121]
	v_cvt_pk_bf16_f32 v122, v122, s0
	global_store_short v[120:121], v122, off
	v_mul_f32_e32 v122, 0x45800000, v136
	v_or_b32_e32 v140, 19, v200
	v_cndmask_b32_e32 v143, v136, v122, vcc
	v_ashrrev_i32_e32 v141, 31, v140
	v_mul_f32_e32 v122, v123, v143
	s_waitcnt vmcnt(21)
	v_pk_fma_f32 v[138:139], v[174:175], s[16:17], v[204:205] op_sel_hi:[1,0,0]
	v_cvt_pk_bf16_f32 v136, v122, s0
	v_lshlrev_b64 v[122:123], 11, v[140:141]
	v_mul_f32_e32 v140, 0x4b800000, v138
	v_cmp_gt_f32_e32 vcc, s27, v138
	s_nop 0
	v_lshl_add_u64 v[122:123], v[202:203], 0, v[122:123]
	v_cndmask_b32_e32 v138, v138, v140, vcc
	v_rsq_f32_e32 v132, v138
	global_store_short v[122:123], v136, off
	v_or_b32_e32 v136, 24, v200
	v_ashrrev_i32_e32 v137, 31, v136
	v_lshlrev_b64 v[136:137], 11, v[136:137]
	v_mul_f32_e32 v133, 0x45800000, v132
	s_nop 0
	global_store_short v[156:157], v84, off offset:128
	v_mul_f32_e32 v84, v88, v154
	v_cvt_pk_bf16_f32 v84, v84, s0
	v_cvt_pk_bf16_f32 v64, v64, s0
	global_store_short v[158:159], v84, off offset:128
	v_mul_f32_e32 v84, v89, v155
	global_store_short v[156:157], v64, off offset:192
	s_nop 0
	v_lshl_add_u64 v[128:129], v[202:203], 0, v[136:137]
	v_cndmask_b32_e32 v136, v132, v133, vcc
	v_mul_f32_e32 v132, 0x4b800000, v139
	v_cmp_gt_f32_e32 vcc, s27, v139
	v_mul_f32_e32 v124, v124, v136
	v_cvt_pk_bf16_f32 v124, v124, s0
	v_cndmask_b32_e32 v132, v139, v132, vcc
	v_rsq_f32_e32 v132, v132
	global_store_short v[128:129], v124, off
	v_or_b32_e32 v130, 25, v200
	v_ashrrev_i32_e32 v131, 31, v130
	v_mul_f32_e32 v124, 0x45800000, v132
	v_cndmask_b32_e32 v137, v132, v124, vcc
	v_mul_f32_e32 v124, v125, v137
	v_cvt_pk_bf16_f32 v132, v124, s0
	v_lshlrev_b64 v[124:125], 11, v[130:131]
	v_lshl_add_u64 v[124:125], v[202:203], 0, v[124:125]
	global_store_short v[124:125], v132, off
	v_pk_fma_f32 v[132:133], v[176:177], s[16:17], v[204:205] op_sel_hi:[1,0,0]
	v_mul_f32_e32 v64, v72, v154
	v_mul_f32_e32 v134, 0x4b800000, v132
	v_cmp_gt_f32_e32 vcc, s27, v132
	v_cvt_pk_bf16_f32 v84, v84, s0
	v_cvt_pk_bf16_f32 v64, v64, s0
	v_cndmask_b32_e32 v132, v132, v134, vcc
	v_rsq_f32_e32 v132, v132
	v_or_b32_e32 v130, 26, v200
	global_store_short v[118:119], v84, off offset:128
	v_mul_f32_e32 v84, v90, v142
	v_mul_f32_e32 v138, 0x45800000, v132
	v_cndmask_b32_e32 v132, v132, v138, vcc
	v_mul_f32_e32 v138, 0x4b800000, v133
	v_cmp_gt_f32_e32 vcc, s27, v133
	global_store_short v[158:159], v64, off offset:192
	v_mul_f32_e32 v64, v73, v155
	v_cndmask_b32_e32 v133, v133, v138, vcc
	v_rsq_f32_e32 v133, v133
	v_ashrrev_i32_e32 v131, 31, v130
	v_cvt_pk_bf16_f32 v84, v84, s0
	v_cvt_pk_bf16_f32 v64, v64, s0
	v_lshlrev_b64 v[130:131], 11, v[130:131]
	v_mul_f32_e32 v126, v126, v132
	global_store_short v[120:121], v84, off offset:128
	v_mul_f32_e32 v84, v91, v143
	global_store_short v[118:119], v64, off offset:192
	v_mul_f32_e32 v64, v74, v142
	v_lshl_add_u64 v[130:131], v[202:203], 0, v[130:131]
	v_cvt_pk_bf16_f32 v126, v126, s0
	v_cvt_pk_bf16_f32 v84, v84, s0
	v_cvt_pk_bf16_f32 v64, v64, s0
	global_store_short v[130:131], v126, off
	v_mul_f32_e32 v126, 0x45800000, v133
	global_store_short v[122:123], v84, off offset:128
	v_mul_f32_e32 v84, v92, v136
	global_store_short v[120:121], v64, off offset:192
	v_mul_f32_e32 v64, v75, v143
	s_waitcnt vmcnt(26)
; DI bfr f2bf(float a) { return (bfr)(pack2(a, 0.f) & 0xffffu); }
; DI int crow(int reg, int h) { return (reg & 3) + 8 * (reg >> 2) + 4 * h; }
; template <int lda, class Epi>
; DI void gemm_tile(const bfr* __restrict__ A, const bfr* __restrict__ Bt, int NB, int K, int m0, int n0, char* smem, Epi epi) {
;     ...
; #pragma unroll
;   for (int i = 0; i < 2; ++i)
; #pragma unroll
;     for (int j = 0; j < 4; ++j)
; #pragma unroll
;       for (int q = 0; q < 16; ++q) {
;         int row = m0 + wr * 64 + i * 32 + crow(q, hl);
;         int col = n0 + wc * 128 + j * 32 + r;
;         epi(row, col, acc[i][j][q]);
;       }
; DI void phase_gemm_bf16out(const Params& p, const bfr* A, const bfr* Wt, bfr* C, int N, const float* ss, char* smem) {
;     ...
;   for (int t0 = blockIdx.x; t0 < 128 * ntn; t0 += gridDim.x) {
;     const int t = ((gridDim.x & 7) == 0) ? xcd_tile(t0, ntn) : t0;
;     int mt = t / ntn, nt = t % ntn;
;     gemm_tile<1024>(A, Wt, N, 1024, mt * 128, nt * 256, smem,
;               [=](int row, int col, float v) {
;                 float inv = rsqrtf(ss[row] * (1.0f / 1024.0f) + EPSF);
;                 C[(size_t)row * N + col] = f2bf(v * inv);
;               });
	v_pk_fma_f32 v[66:67], v[80:81], s[16:17], v[204:205] op_sel_hi:[1,0,0]
	v_cndmask_b32_e32 v133, v133, v126, vcc
	v_cvt_pk_bf16_f32 v84, v84, s0
	v_cvt_pk_bf16_f32 v64, v64, s0
	v_mul_f32_e32 v72, 0x4b800000, v66
	v_cmp_gt_f32_e32 vcc, s27, v66
	global_store_short v[128:129], v84, off offset:128
	v_mul_f32_e32 v84, v93, v137
	global_store_short v[122:123], v64, off offset:192
	v_mul_f32_e32 v64, v76, v136
	v_cndmask_b32_e32 v66, v66, v72, vcc
	v_cvt_pk_bf16_f32 v84, v84, s0
	v_cvt_pk_bf16_f32 v64, v64, s0
	v_rsq_f32_e32 v66, v66
	v_or_b32_e32 v134, 27, v200
	global_store_short v[124:125], v84, off offset:128
	v_mul_f32_e32 v84, v94, v132
	global_store_short v[128:129], v64, off offset:192
	v_mul_f32_e32 v64, v77, v137
	v_ashrrev_i32_e32 v135, 31, v134
	v_mul_f32_e32 v126, v127, v133
	v_cvt_pk_bf16_f32 v84, v84, s0
	v_cvt_pk_bf16_f32 v64, v64, s0
	v_cvt_pk_bf16_f32 v138, v126, s0
	v_lshlrev_b64 v[126:127], 11, v[134:135]
	global_store_short v[130:131], v84, off offset:128
	v_mul_f32_e32 v84, v95, v133
	global_store_short v[124:125], v64, off offset:192
	v_mul_f32_e32 v64, v78, v132
	v_lshl_add_u64 v[126:127], v[202:203], 0, v[126:127]
	v_cvt_pk_bf16_f32 v84, v84, s0
	v_cvt_pk_bf16_f32 v64, v64, s0
	v_mul_f32_e32 v74, 0x45800000, v66
	global_store_short v[126:127], v84, off offset:128
	global_store_short v[130:131], v64, off offset:192
	v_mul_f32_e32 v64, v79, v133
	v_cndmask_b32_e32 v84, v66, v74, vcc
	v_mul_f32_e32 v66, 0x4b800000, v67
	v_cmp_gt_f32_e32 vcc, s27, v67
	v_cvt_pk_bf16_f32 v64, v64, s0
	global_store_short v[126:127], v64, off offset:192
	v_cndmask_b32_e32 v66, v67, v66, vcc
	v_or_b32_e32 v64, 32, v200
	v_rsq_f32_e32 v66, v66
	v_ashrrev_i32_e32 v65, 31, v64
	v_lshlrev_b64 v[64:65], 11, v[64:65]
	v_mul_f32_e32 v48, v48, v84
	v_lshl_add_u64 v[64:65], v[202:203], 0, v[64:65]
	v_cvt_pk_bf16_f32 v48, v48, s0
	global_store_short v[64:65], v48, off
	v_mul_f32_e32 v48, 0x45800000, v66
	v_pk_fma_f32 v[76:77], v[82:83], s[16:17], v[204:205] op_sel_hi:[1,0,0]
	v_cndmask_b32_e32 v85, v66, v48, vcc
	v_mul_f32_e32 v78, 0x4b800000, v76
	v_cmp_gt_f32_e32 vcc, s27, v76
	v_or_b32_e32 v72, 33, v200
	v_ashrrev_i32_e32 v73, 31, v72
	v_cndmask_b32_e32 v76, v76, v78, vcc
	v_mul_f32_e32 v48, v49, v85
	v_rsq_f32_e32 v76, v76
	v_cvt_pk_bf16_f32 v66, v48, s0
	v_lshlrev_b64 v[48:49], 11, v[72:73]
	global_load_dwordx4 v[72:75], v[206:207], off offset:192
	v_mul_f32_e32 v80, 0x45800000, v76
	v_cndmask_b32_e32 v86, v76, v80, vcc
	v_mul_f32_e32 v76, 0x4b800000, v77
	v_cmp_gt_f32_e32 vcc, s27, v77
	v_lshl_add_u64 v[48:49], v[202:203], 0, v[48:49]
	global_store_short v[48:49], v66, off
	v_cndmask_b32_e32 v76, v77, v76, vcc
	v_or_b32_e32 v66, 34, v200
	v_rsq_f32_e32 v76, v76
	v_ashrrev_i32_e32 v67, 31, v66
	v_lshlrev_b64 v[66:67], 11, v[66:67]
	v_mul_f32_e32 v50, v50, v86
	v_lshl_add_u64 v[66:67], v[202:203], 0, v[66:67]
	v_cvt_pk_bf16_f32 v50, v50, s0
	global_store_short v[66:67], v50, off
	v_mul_f32_e32 v50, 0x45800000, v76
	v_or_b32_e32 v78, 35, v200
	v_cndmask_b32_e32 v87, v76, v50, vcc
	v_ashrrev_i32_e32 v79, 31, v78
	v_mul_f32_e32 v50, v51, v87
	v_cvt_pk_bf16_f32 v76, v50, s0
	v_lshlrev_b64 v[50:51], 11, v[78:79]
	s_waitcnt vmcnt(28)
	v_pk_fma_f32 v[78:79], v[68:69], s[16:17], v[204:205] op_sel_hi:[1,0,0]
	v_lshl_add_u64 v[50:51], v[202:203], 0, v[50:51]
	v_mul_f32_e32 v68, 0x4b800000, v78
	v_cmp_gt_f32_e32 vcc, s27, v78
	global_store_short v[50:51], v76, off
	v_or_b32_e32 v76, 40, v200
	v_cndmask_b32_e32 v68, v78, v68, vcc
	v_rsq_f32_e32 v78, v68
	v_ashrrev_i32_e32 v77, 31, v76
	v_lshlrev_b64 v[76:77], 11, v[76:77]
	v_lshl_add_u64 v[68:69], v[202:203], 0, v[76:77]
	v_mul_f32_e32 v80, 0x45800000, v78
	v_cndmask_b32_e32 v88, v78, v80, vcc
	v_mul_f32_e32 v78, 0x4b800000, v79
	v_cmp_gt_f32_e32 vcc, s27, v79
	v_mul_f32_e32 v52, v52, v88
	v_cvt_pk_bf16_f32 v52, v52, s0
	v_cndmask_b32_e32 v78, v79, v78, vcc
	v_rsq_f32_e32 v78, v78
	global_store_short v[68:69], v52, off
	v_or_b32_e32 v76, 41, v200
	v_ashrrev_i32_e32 v77, 31, v76
	v_mul_f32_e32 v52, 0x45800000, v78
	v_cndmask_b32_e32 v89, v78, v52, vcc
	v_mul_f32_e32 v52, v53, v89
	v_cvt_pk_bf16_f32 v78, v52, s0
	v_lshlrev_b64 v[52:53], 11, v[76:77]
	v_or_b32_e32 v76, 42, v200
	v_lshl_add_u64 v[52:53], v[202:203], 0, v[52:53]
	v_ashrrev_i32_e32 v77, 31, v76
	global_store_short v[52:53], v78, off
	v_lshlrev_b64 v[80:81], 11, v[76:77]
	global_load_dwordx4 v[76:79], v[206:207], off offset:224
	v_pk_fma_f32 v[82:83], v[70:71], s[16:17], v[204:205] op_sel_hi:[1,0,0]
	v_mul_f32_e32 v96, v96, v198
	v_mul_f32_e32 v70, 0x4b800000, v82
	v_cmp_gt_f32_e32 vcc, s27, v82
	v_cvt_pk_bf16_f32 v96, v96, s0
	global_store_short v[210:211], v96, off offset:64
	v_cndmask_b32_e32 v70, v82, v70, vcc
	v_rsq_f32_e32 v82, v70
	v_lshl_add_u64 v[70:71], v[202:203], 0, v[80:81]
	v_or_b32_e32 v80, 43, v200
	v_ashrrev_i32_e32 v81, 31, v80
	v_mul_f32_e32 v90, 0x45800000, v82
	v_cndmask_b32_e32 v90, v82, v90, vcc
	v_mul_f32_e32 v82, 0x4b800000, v83
	v_cmp_gt_f32_e32 vcc, s27, v83
	v_mul_f32_e32 v54, v54, v90
	v_cvt_pk_bf16_f32 v54, v54, s0
	v_cndmask_b32_e32 v82, v83, v82, vcc
	v_rsq_f32_e32 v82, v82
	global_store_short v[70:71], v54, off
	v_mul_f32_e32 v96, v97, v197
	v_cvt_pk_bf16_f32 v96, v96, s0
	v_mul_f32_e32 v54, 0x45800000, v82
	v_cndmask_b32_e32 v91, v82, v54, vcc
	v_mul_f32_e32 v54, v55, v91
	v_cvt_pk_bf16_f32 v82, v54, s0
	v_lshlrev_b64 v[54:55], 11, v[80:81]
	v_lshl_add_u64 v[54:55], v[202:203], 0, v[54:55]
	s_waitcnt vmcnt(8)
; DI bfr f2bf(float a) { return (bfr)(pack2(a, 0.f) & 0xffffu); }
; DI int crow(int reg, int h) { return (reg & 3) + 8 * (reg >> 2) + 4 * h; }
; template <int lda, class Epi>
; DI void gemm_tile(const bfr* __restrict__ A, const bfr* __restrict__ Bt, int NB, int K, int m0, int n0, char* smem, Epi epi) {
;     ...
; #pragma unroll
;   for (int i = 0; i < 2; ++i)
; #pragma unroll
;     for (int j = 0; j < 4; ++j)
; #pragma unroll
;       for (int q = 0; q < 16; ++q) {
;         int row = m0 + wr * 64 + i * 32 + crow(q, hl);
;         int col = n0 + wc * 128 + j * 32 + r;
;         epi(row, col, acc[i][j][q]);
;       }
; DI void phase_gemm_bf16out(const Params& p, const bfr* A, const bfr* Wt, bfr* C, int N, const float* ss, char* smem) {
;     ...
;   for (int t0 = blockIdx.x; t0 < 128 * ntn; t0 += gridDim.x) {
;     const int t = ((gridDim.x & 7) == 0) ? xcd_tile(t0, ntn) : t0;
;     int mt = t / ntn, nt = t % ntn;
;     gemm_tile<1024>(A, Wt, N, 1024, mt * 128, nt * 256, smem,
;               [=](int row, int col, float v) {
;                 float inv = rsqrtf(ss[row] * (1.0f / 1024.0f) + EPSF);
;                 C[(size_t)row * N + col] = f2bf(v * inv);
;               });
	v_pk_fma_f32 v[72:73], v[72:73], s[16:17], v[204:205] op_sel_hi:[1,0,0]
	global_store_short v[54:55], v82, off
	v_mul_f32_e32 v82, 0x4b800000, v72
	v_cmp_gt_f32_e32 vcc, s27, v72
	v_or_b32_e32 v80, 48, v200
	global_store_short v[212:213], v96, off offset:64
	v_cndmask_b32_e32 v72, v72, v82, vcc
	v_rsq_f32_e32 v72, v72
	v_mul_f32_e32 v96, v98, v201
	v_ashrrev_i32_e32 v81, 31, v80
	v_cvt_pk_bf16_f32 v96, v96, s0
	v_mul_f32_e32 v92, 0x45800000, v72
	v_cndmask_b32_e32 v92, v72, v92, vcc
	v_mul_f32_e32 v72, 0x4b800000, v73
	v_cmp_gt_f32_e32 vcc, s27, v73
	v_lshlrev_b64 v[80:81], 11, v[80:81]
	v_mul_f32_e32 v56, v56, v92
	v_cndmask_b32_e32 v72, v73, v72, vcc
	v_rsq_f32_e32 v72, v72
	global_store_short v[208:209], v96, off offset:64
	v_mul_f32_e32 v96, v99, v222
	v_lshl_add_u64 v[80:81], v[202:203], 0, v[80:81]
	v_cvt_pk_bf16_f32 v56, v56, s0
	v_cvt_pk_bf16_f32 v96, v96, s0
	global_store_short v[80:81], v56, off
	v_mul_f32_e32 v56, 0x45800000, v72
	global_store_short v[112:113], v96, off offset:64
	v_mul_f32_e32 v96, v100, v188
	v_or_b32_e32 v82, 49, v200
	v_cndmask_b32_e32 v93, v72, v56, vcc
	v_cvt_pk_bf16_f32 v96, v96, s0
	v_ashrrev_i32_e32 v83, 31, v82
	v_mul_f32_e32 v56, v57, v93
	v_pk_fma_f32 v[74:75], v[74:75], s[16:17], v[204:205] op_sel_hi:[1,0,0]
	global_store_short v[114:115], v96, off offset:64
	v_mul_f32_e32 v96, v101, v182
	v_cvt_pk_bf16_f32 v72, v56, s0
	v_lshlrev_b64 v[56:57], 11, v[82:83]
	v_mul_f32_e32 v82, 0x4b800000, v74
	v_cmp_gt_f32_e32 vcc, s27, v74
	v_cvt_pk_bf16_f32 v96, v96, s0
	global_store_short v[116:117], v96, off offset:64
	v_cndmask_b32_e32 v74, v74, v82, vcc
	v_mul_f32_e32 v96, v102, v178
	v_rsq_f32_e32 v74, v74
	v_cvt_pk_bf16_f32 v96, v96, s0
	global_store_short v[172:173], v96, off offset:64
	v_mul_f32_e32 v96, v103, v179
	v_cvt_pk_bf16_f32 v96, v96, s0
	global_store_short v[156:157], v96, off offset:64
	v_mul_f32_e32 v96, v104, v154
	v_mul_f32_e32 v94, 0x45800000, v74
	v_cvt_pk_bf16_f32 v96, v96, s0
	v_cndmask_b32_e32 v94, v74, v94, vcc
	v_mul_f32_e32 v74, 0x4b800000, v75
	v_cmp_gt_f32_e32 vcc, s27, v75
	global_store_short v[158:159], v96, off offset:64
	v_mul_f32_e32 v96, v105, v155
	v_lshl_add_u64 v[56:57], v[202:203], 0, v[56:57]
	v_cndmask_b32_e32 v74, v75, v74, vcc
	v_cvt_pk_bf16_f32 v96, v96, s0
	global_store_short v[56:57], v72, off
	v_or_b32_e32 v72, 50, v200
	v_rsq_f32_e32 v74, v74
	global_store_short v[118:119], v96, off offset:64
	v_mul_f32_e32 v96, v106, v142
	v_ashrrev_i32_e32 v73, 31, v72
	v_cvt_pk_bf16_f32 v96, v96, s0
	v_lshlrev_b64 v[72:73], 11, v[72:73]
	v_mul_f32_e32 v58, v58, v94
	global_store_short v[120:121], v96, off offset:64
	v_mul_f32_e32 v96, v107, v143
	v_lshl_add_u64 v[72:73], v[202:203], 0, v[72:73]
	v_cvt_pk_bf16_f32 v58, v58, s0
	v_cvt_pk_bf16_f32 v96, v96, s0
	global_store_short v[72:73], v58, off
	v_mul_f32_e32 v58, 0x45800000, v74
	global_store_short v[122:123], v96, off offset:64
	v_mul_f32_e32 v96, v108, v136
	v_or_b32_e32 v82, 51, v200
	v_cndmask_b32_e32 v95, v74, v58, vcc
	v_cvt_pk_bf16_f32 v96, v96, s0
	v_ashrrev_i32_e32 v83, 31, v82
	v_mul_f32_e32 v58, v59, v95
	s_waitcnt vmcnt(17)
	v_pk_fma_f32 v[76:77], v[76:77], s[16:17], v[204:205] op_sel_hi:[1,0,0]
	global_store_short v[128:129], v96, off offset:64
	v_mul_f32_e32 v96, v109, v137
	v_cvt_pk_bf16_f32 v74, v58, s0
	v_lshlrev_b64 v[58:59], 11, v[82:83]
	v_mul_f32_e32 v82, 0x4b800000, v76
	v_cmp_gt_f32_e32 vcc, s27, v76
	v_cvt_pk_bf16_f32 v96, v96, s0
	global_store_short v[124:125], v96, off offset:64
	v_cndmask_b32_e32 v76, v76, v82, vcc
	v_mul_f32_e32 v96, v110, v132
	v_rsq_f32_e32 v76, v76
	v_mul_f32_e32 v32, v32, v84
	v_mul_f32_e32 v16, v16, v84
	v_mul_f32_e32 v0, v0, v84
	v_cvt_pk_bf16_f32 v96, v96, s0
	v_cvt_pk_bf16_f32 v32, v32, s0
	v_cvt_pk_bf16_f32 v16, v16, s0
	v_cvt_pk_bf16_f32 v0, v0, s0
	global_store_short v[130:131], v96, off offset:64
	v_mul_f32_e32 v96, v111, v133
	global_store_short v[64:65], v32, off offset:64
	v_mul_f32_e32 v32, v33, v85
	global_store_short v[64:65], v16, off offset:128
	v_mul_f32_e32 v16, v17, v85
	global_store_short v[64:65], v0, off offset:192
	v_mul_f32_e32 v0, v1, v85
	v_cvt_pk_bf16_f32 v96, v96, s0
	v_cvt_pk_bf16_f32 v32, v32, s0
	v_cvt_pk_bf16_f32 v16, v16, s0
	v_cvt_pk_bf16_f32 v0, v0, s0
	global_store_short v[126:127], v96, off offset:64
	v_mul_f32_e32 v96, 0x45800000, v76
	global_store_short v[48:49], v32, off offset:64
	v_mul_f32_e32 v32, v34, v86
	global_store_short v[48:49], v16, off offset:128
	v_mul_f32_e32 v16, v18, v86
	global_store_short v[48:49], v0, off offset:192
	v_mul_f32_e32 v0, v2, v86
	v_cndmask_b32_e32 v96, v76, v96, vcc
	v_mul_f32_e32 v76, 0x4b800000, v77
	v_cmp_gt_f32_e32 vcc, s27, v77
	v_cvt_pk_bf16_f32 v32, v32, s0
	v_cvt_pk_bf16_f32 v16, v16, s0
	v_cvt_pk_bf16_f32 v0, v0, s0
	v_lshl_add_u64 v[58:59], v[202:203], 0, v[58:59]
	v_cndmask_b32_e32 v76, v77, v76, vcc
	global_store_short v[66:67], v32, off offset:64
	v_mul_f32_e32 v32, v35, v87
	global_store_short v[66:67], v16, off offset:128
	v_mul_f32_e32 v16, v19, v87
	global_store_short v[66:67], v0, off offset:192
	v_mul_f32_e32 v0, v3, v87
	global_store_short v[58:59], v74, off
	v_or_b32_e32 v74, 56, v200
	v_rsq_f32_e32 v76, v76
	v_cvt_pk_bf16_f32 v32, v32, s0
	v_cvt_pk_bf16_f32 v16, v16, s0
	v_cvt_pk_bf16_f32 v0, v0, s0
	v_ashrrev_i32_e32 v75, 31, v74
	global_store_short v[50:51], v32, off offset:64
	v_mul_f32_e32 v32, v36, v88
	global_store_short v[50:51], v16, off offset:128
	v_mul_f32_e32 v16, v20, v88
; DI bfr f2bf(float a) { return (bfr)(pack2(a, 0.f) & 0xffffu); }
; DI int crow(int reg, int h) { return (reg & 3) + 8 * (reg >> 2) + 4 * h; }
; template <int lda, class Epi>
; DI void gemm_tile(const bfr* __restrict__ A, const bfr* __restrict__ Bt, int NB, int K, int m0, int n0, char* smem, Epi epi) {
;     ...
; #pragma unroll
;   for (int i = 0; i < 2; ++i)
; #pragma unroll
;     for (int j = 0; j < 4; ++j)
; #pragma unroll
;       for (int q = 0; q < 16; ++q) {
;         int row = m0 + wr * 64 + i * 32 + crow(q, hl);
;         int col = n0 + wc * 128 + j * 32 + r;
;         epi(row, col, acc[i][j][q]);
;       }
; DI void phase_gemm_bf16out(const Params& p, const bfr* A, const bfr* Wt, bfr* C, int N, const float* ss, char* smem) {
;     ...
;   for (int t0 = blockIdx.x; t0 < 128 * ntn; t0 += gridDim.x) {
;     const int t = ((gridDim.x & 7) == 0) ? xcd_tile(t0, ntn) : t0;
;     int mt = t / ntn, nt = t % ntn;
;     gemm_tile<1024>(A, Wt, N, 1024, mt * 128, nt * 256, smem,
;               [=](int row, int col, float v) {
;                 float inv = rsqrtf(ss[row] * (1.0f / 1024.0f) + EPSF);
;                 C[(size_t)row * N + col] = f2bf(v * inv);
;               });
	global_store_short v[50:51], v0, off offset:192
	v_mul_f32_e32 v0, v4, v88
	v_lshlrev_b64 v[74:75], 11, v[74:75]
	v_mul_f32_e32 v60, v60, v96
	v_cvt_pk_bf16_f32 v32, v32, s0
	v_cvt_pk_bf16_f32 v16, v16, s0
	v_cvt_pk_bf16_f32 v0, v0, s0
	v_lshl_add_u64 v[74:75], v[202:203], 0, v[74:75]
	v_cvt_pk_bf16_f32 v60, v60, s0
	global_store_short v[68:69], v32, off offset:64
	v_mul_f32_e32 v32, v37, v89
	global_store_short v[68:69], v16, off offset:128
	v_mul_f32_e32 v16, v21, v89
	global_store_short v[68:69], v0, off offset:192
	v_mul_f32_e32 v0, v5, v89
	global_store_short v[74:75], v60, off
	v_mul_f32_e32 v60, 0x45800000, v76
	v_cvt_pk_bf16_f32 v32, v32, s0
	v_cvt_pk_bf16_f32 v16, v16, s0
	v_cvt_pk_bf16_f32 v0, v0, s0
	v_or_b32_e32 v82, 57, v200
	v_cndmask_b32_e32 v97, v76, v60, vcc
	global_store_short v[52:53], v32, off offset:64
	v_mul_f32_e32 v32, v38, v90
	global_store_short v[52:53], v16, off offset:128
	v_mul_f32_e32 v16, v22, v90
	global_store_short v[52:53], v0, off offset:192
	v_mul_f32_e32 v0, v6, v90
	v_ashrrev_i32_e32 v83, 31, v82
	v_mul_f32_e32 v60, v61, v97
	v_pk_fma_f32 v[78:79], v[78:79], s[16:17], v[204:205] op_sel_hi:[1,0,0]
	v_cvt_pk_bf16_f32 v32, v32, s0
	v_cvt_pk_bf16_f32 v16, v16, s0
	v_cvt_pk_bf16_f32 v0, v0, s0
	v_cvt_pk_bf16_f32 v76, v60, s0
	v_lshlrev_b64 v[60:61], 11, v[82:83]
	v_mul_f32_e32 v82, 0x4b800000, v78
	v_cmp_gt_f32_e32 vcc, s27, v78
	global_store_short v[70:71], v32, off offset:64
	v_mul_f32_e32 v32, v39, v91
	global_store_short v[70:71], v16, off offset:128
	v_mul_f32_e32 v16, v23, v91
	global_store_short v[70:71], v0, off offset:192
	v_mul_f32_e32 v0, v7, v91
	v_cndmask_b32_e32 v78, v78, v82, vcc
	v_cvt_pk_bf16_f32 v32, v32, s0
	v_cvt_pk_bf16_f32 v16, v16, s0
	v_cvt_pk_bf16_f32 v0, v0, s0
	v_rsq_f32_e32 v78, v78
	global_store_short v[54:55], v32, off offset:64
	v_mul_f32_e32 v32, v40, v92
	global_store_short v[54:55], v16, off offset:128
	v_mul_f32_e32 v16, v24, v92
	global_store_short v[54:55], v0, off offset:192
	v_mul_f32_e32 v0, v8, v92
	v_cvt_pk_bf16_f32 v32, v32, s0
	v_cvt_pk_bf16_f32 v16, v16, s0
	v_cvt_pk_bf16_f32 v0, v0, s0
	global_store_short v[80:81], v32, off offset:64
	v_mul_f32_e32 v32, v41, v93
	global_store_short v[80:81], v16, off offset:128
	v_mul_f32_e32 v16, v25, v93
	global_store_short v[80:81], v0, off offset:192
	v_mul_f32_e32 v0, v9, v93
	v_cvt_pk_bf16_f32 v32, v32, s0
	v_cvt_pk_bf16_f32 v16, v16, s0
	v_cvt_pk_bf16_f32 v0, v0, s0
	v_mul_f32_e32 v98, 0x45800000, v78
	global_store_short v[56:57], v32, off offset:64
	v_mul_f32_e32 v32, v42, v94
	global_store_short v[56:57], v16, off offset:128
	v_mul_f32_e32 v16, v26, v94
	global_store_short v[56:57], v0, off offset:192
	v_mul_f32_e32 v0, v10, v94
	v_cndmask_b32_e32 v78, v78, v98, vcc
	v_mul_f32_e32 v98, 0x4b800000, v79
	v_cmp_gt_f32_e32 vcc, s27, v79
	v_cvt_pk_bf16_f32 v32, v32, s0
	v_cvt_pk_bf16_f32 v16, v16, s0
	v_cvt_pk_bf16_f32 v0, v0, s0
	v_lshl_add_u64 v[60:61], v[202:203], 0, v[60:61]
	v_cndmask_b32_e32 v79, v79, v98, vcc
	global_store_short v[72:73], v32, off offset:64
	v_mul_f32_e32 v32, v43, v95
	global_store_short v[72:73], v16, off offset:128
	v_mul_f32_e32 v16, v27, v95
	global_store_short v[72:73], v0, off offset:192
	v_mul_f32_e32 v0, v11, v95
	global_store_short v[60:61], v76, off
	v_or_b32_e32 v76, 58, v200
	v_rsq_f32_e32 v79, v79
	v_cvt_pk_bf16_f32 v32, v32, s0
	v_cvt_pk_bf16_f32 v16, v16, s0
	v_cvt_pk_bf16_f32 v0, v0, s0
	v_ashrrev_i32_e32 v77, 31, v76
	global_store_short v[58:59], v32, off offset:64
	v_mul_f32_e32 v32, v44, v96
	global_store_short v[58:59], v16, off offset:128
	v_mul_f32_e32 v16, v28, v96
	global_store_short v[58:59], v0, off offset:192
	v_mul_f32_e32 v0, v12, v96
	v_lshlrev_b64 v[76:77], 11, v[76:77]
	v_mul_f32_e32 v62, v62, v78
	v_cvt_pk_bf16_f32 v32, v32, s0
	v_cvt_pk_bf16_f32 v16, v16, s0
	v_cvt_pk_bf16_f32 v0, v0, s0
	v_lshl_add_u64 v[76:77], v[202:203], 0, v[76:77]
	v_cvt_pk_bf16_f32 v62, v62, s0
	global_store_short v[74:75], v32, off offset:64
	v_mul_f32_e32 v32, v45, v97
	global_store_short v[74:75], v16, off offset:128
	v_mul_f32_e32 v16, v29, v97
	global_store_short v[74:75], v0, off offset:192
	v_mul_f32_e32 v0, v13, v97
	global_store_short v[76:77], v62, off
	v_mul_f32_e32 v62, 0x45800000, v79
	v_cvt_pk_bf16_f32 v32, v32, s0
	v_cvt_pk_bf16_f32 v16, v16, s0
	v_cvt_pk_bf16_f32 v0, v0, s0
	v_or_b32_e32 v82, 59, v200
	v_cndmask_b32_e32 v79, v79, v62, vcc
	global_store_short v[60:61], v32, off offset:64
	v_mul_f32_e32 v32, v46, v78
	global_store_short v[60:61], v16, off offset:128
	v_mul_f32_e32 v16, v30, v78
	global_store_short v[60:61], v0, off offset:192
	v_mul_f32_e32 v0, v14, v78
	v_ashrrev_i32_e32 v83, 31, v82
	v_mul_f32_e32 v62, v63, v79
	v_cvt_pk_bf16_f32 v32, v32, s0
	v_cvt_pk_bf16_f32 v16, v16, s0
	v_cvt_pk_bf16_f32 v0, v0, s0
	v_cvt_pk_bf16_f32 v98, v62, s0
	v_lshlrev_b64 v[62:63], 11, v[82:83]
	global_store_short v[76:77], v32, off offset:64
	v_mul_f32_e32 v32, v47, v79
	global_store_short v[76:77], v16, off offset:128
	v_mul_f32_e32 v16, v31, v79
	global_store_short v[76:77], v0, off offset:192
	v_mul_f32_e32 v0, v15, v79
	v_lshl_add_u64 v[62:63], v[202:203], 0, v[62:63]
	v_cvt_pk_bf16_f32 v32, v32, s0
	v_cvt_pk_bf16_f32 v16, v16, s0
	v_cvt_pk_bf16_f32 v0, v0, s0
	global_store_short v[126:127], v138, off
	global_store_short v[62:63], v98, off
	global_store_short v[62:63], v32, off offset:64
	global_store_short v[62:63], v16, off offset:128
	global_store_short v[62:63], v0, off offset:192
	s_cbranch_scc0 .LBB0_936

; #define GA_LOAD(pr_) do { _Pragma("unroll") for (int i = 0; i < 4; ++i) ra[i] = *(const u32x4*)(Ab + (i * 32) * lda + (pr_) * 64); } while (0)
; #define GB_LOAD(kt_) do { const bfr* bk_ = Bb + (kt_) * NB * 32; \
;     _Pragma("unroll") for (int i = 0; i < 4; ++i) rb[i] = *(const u32x4*)(bk_ + (i * 64) * 32); } while (0)
; #define G_STORE(kt_) do { bfr* as_ = S0 + ((kt_) & 1) * GSTAGE; bfr* bs_ = as_ + 128 * 40; \
;     if (apar == ((kt_) & 1)) { _Pragma("unroll") for (int i = 0; i < 4; ++i) *(u32x4*)(as_ + asoff + i * 32 * 40) = ra[i]; } \
;     _Pragma("unroll") for (int i = 0; i < 4; ++i) *(u32x4*)(bs_ + bsoff + i * 64 * 40) = rb[i]; } while (0)
; template <int lda>
; DI void gemm_mainloop(const bfr* __restrict__ A, const bfr* __restrict__ Bt, int NB, int K, int m0, int n0, char* smem, f32x16 (&acc)[2][4]) {
;   bfr* S0 = (bfr*)smem;
;   int tid = threadIdx.x;
;   asm volatile("" : "+v"(tid));
;   const int lane = tid & 63, wid = tid >> 6, wr = wid >> 1, wc = wid & 1;
;   const int r = lane & 31, hl = lane >> 5;
; #pragma unroll
;   for (int i = 0; i < 2; ++i)
; #pragma unroll
;     for (int j = 0; j < 4; ++j)
; #pragma unroll
;       for (int q = 0; q < 16; ++q) acc[i][j][q] = 0.f;
;   u32x4 ra[4], rb[4];
;   const int nk = K >> 5;
;   const int arow = tid >> 3, ac8 = tid & 7, apar = ac8 >> 2;
;   const bfr* Ab = A + (m0 + arow) * lda + ac8 * 8;
;   const int asoff = arow * 40 + (ac8 & 3) * 8;
;   const int brow = tid >> 2, bc4 = tid & 3;
;   const bfr* Bb = Bt + (n0 + brow) * 32 + bc4 * 8;
;   const int bsoff = brow * 40 + bc4 * 8;
;     ...
;   GA_LOAD(0);
;   GB_LOAD(0);
;   G_STORE(0);
;   GB_LOAD(1);
;   __syncthreads();
.LBB0_925:
	s_ashr_i32 s5, s4, 31
	s_lshr_b32 s5, s5, 30
	s_add_i32 s5, s4, s5
	s_and_b32 s6, s5, 0xfffffc
	s_lshl_b32 s5, s5, 5
	s_and_b32 s30, s5, 0xffffff80
	s_sub_i32 s4, s4, s6
	s_lshl_b32 s29, s4, 8
	s_lshl_b32 s98, s30, 11
	s_add_u32 s98, s10, s98
	s_addc_u32 s99, s11, 0
	s_lshl_b32 s100, s29, 6
	s_add_u32 s100, s12, s100
	s_addc_u32 s101, s13, 0
	v_writelane_b32 v187, s64, 0
	v_writelane_b32 v187, s65, 1
	v_writelane_b32 v187, s66, 2
	v_writelane_b32 v187, s67, 3
	v_writelane_b32 v187, s68, 4
	v_writelane_b32 v187, s69, 5
	v_writelane_b32 v187, s70, 6
	v_writelane_b32 v187, s71, 7
	v_writelane_b32 v187, s72, 8
	v_writelane_b32 v187, s73, 9
	v_writelane_b32 v187, s74, 10
	v_writelane_b32 v187, s75, 11
	v_writelane_b32 v187, s76, 12
	v_writelane_b32 v187, s77, 13
	v_writelane_b32 v187, s78, 14
	v_writelane_b32 v187, s79, 15
	v_lshrrev_b32_e32 v188, 6, v196
	v_and_b32_e32 v189, 63, v196
	v_readfirstlane_b32 s73, v188
	v_lshrrev_b32_e32 v190, 2, v189
	v_bfe_u32 v191, v189, 4, 2
	v_and_b32_e32 v188, 3, v189
	v_xor_b32_e32 v188, v188, v191
	v_lshlrev_b32_e32 v188, 4, v188
	v_lshl_add_u32 v176, v190, 11, v188
	v_add_u32_e32 v177, 0x8000, v176
	v_lshl_add_u32 v178, v190, 6, v188
	v_and_b32_e32 v190, 31, v189
	v_lshrrev_b32_e32 v191, 5, v189
	v_bfe_u32 v188, v189, 2, 2
	v_xor_b32_e32 v188, v188, v191
	v_lshlrev_b32_e32 v188, 4, v188
	v_lshl_add_u32 v179, v190, 6, v188
	s_lshr_b32 s74, s73, 1
	s_lshl_b32 s74, s74, 12
	s_and_b32 s75, s73, 1
	s_lshl_b32 s75, s75, 13
	v_add_u32_e32 v181, s75, v179
	v_add_u32_e32 v179, s74, v179
	v_xor_b32_e32 v182, 32, v181
	v_xor_b32_e32 v180, 32, v179
	s_lshl_b32 s74, s73, 16
	s_add_u32 s64, s98, s74
	s_addc_u32 s65, s99, 0
	s_lshl_b32 s74, s73, 12
	s_add_u32 s66, s100, s74
	s_addc_u32 s67, s101, 0
	s_lshl_b32 s68, s73, 11
	s_lshl_b32 s69, s73, 12
	s_mov_b32 s70, 0
	s_mov_b32 s71, 0
	s_mov_b32 s72, 0
	s_waitcnt lgkmcnt(0)
	s_barrier
	s_mul_i32 s74, s70, 0x6000
	s_add_u32 s75, s74, s68
	s_mov_b32 m0, s75
	s_add_u32 s76, s74, 0x2000
	s_cmp_eq_u32 s70, 2
	s_cselect_b32 s76, 0x10000, s76
	global_load_lds_dwordx4 v176, s[64:65]
	s_add_u32 m0, s75, 0x400
	s_add_u32 s76, s76, s69
	global_load_lds_dwordx4 v177, s[64:65]
	s_mov_b32 m0, s76
	s_add_u32 s64, s64, 64
	s_addc_u32 s65, s65, 0
	global_load_lds_dwordx4 v178, s[66:67]
	global_load_lds_dwordx4 v178, s[66:67] offset:1024
	global_load_lds_dwordx4 v178, s[66:67] offset:2048
	global_load_lds_dwordx4 v178, s[66:67] offset:3072
	s_add_u32 s66, s66, 0x10000
	s_addc_u32 s67, s67, 0
	s_add_u32 s70, s70, 1
	s_cmp_eq_u32 s70, 3
	s_cselect_b32 s70, 0, s70
	s_mul_i32 s74, s70, 0x6000
	s_add_u32 s75, s74, s68
	s_mov_b32 m0, s75
	s_add_u32 s76, s74, 0x2000
	s_cmp_eq_u32 s70, 2
	s_cselect_b32 s76, 0x10000, s76
	global_load_lds_dwordx4 v176, s[64:65]
	s_add_u32 m0, s75, 0x400
	s_add_u32 s76, s76, s69
	global_load_lds_dwordx4 v177, s[64:65]
	s_mov_b32 m0, s76
	s_add_u32 s64, s64, 64
	s_addc_u32 s65, s65, 0
	global_load_lds_dwordx4 v178, s[66:67]
	global_load_lds_dwordx4 v178, s[66:67] offset:1024
	global_load_lds_dwordx4 v178, s[66:67] offset:2048
	global_load_lds_dwordx4 v178, s[66:67] offset:3072
	s_add_u32 s66, s66, 0x10000
	s_addc_u32 s67, s67, 0
	s_add_u32 s70, s70, 1
	s_cmp_eq_u32 s70, 3
	s_cselect_b32 s70, 0, s70
	v_mov_b32_e32 v112, 0
	v_mov_b32_e32 v113, 0
	v_mov_b32_e32 v114, 0
	v_mov_b32_e32 v115, 0
	v_mov_b32_e32 v116, 0
	v_mov_b32_e32 v117, 0
	v_mov_b32_e32 v118, 0
	v_mov_b32_e32 v119, 0
	v_mov_b32_e32 v120, 0
	v_mov_b32_e32 v121, 0
	v_mov_b32_e32 v122, 0
	v_mov_b32_e32 v123, 0
	v_mov_b32_e32 v124, 0
	v_mov_b32_e32 v125, 0
	v_mov_b32_e32 v126, 0
	v_mov_b32_e32 v127, 0
	v_mov_b32_e32 v96, 0
	v_mov_b32_e32 v97, 0
	v_mov_b32_e32 v98, 0
	v_mov_b32_e32 v99, 0
	v_mov_b32_e32 v100, 0
	v_mov_b32_e32 v101, 0
	v_mov_b32_e32 v102, 0
	v_mov_b32_e32 v103, 0
	v_mov_b32_e32 v104, 0
	v_mov_b32_e32 v105, 0
	v_mov_b32_e32 v106, 0
	v_mov_b32_e32 v107, 0
	v_mov_b32_e32 v108, 0
	v_mov_b32_e32 v109, 0
	v_mov_b32_e32 v110, 0
	v_mov_b32_e32 v111, 0
	v_mov_b32_e32 v80, 0
	v_mov_b32_e32 v81, 0
	v_mov_b32_e32 v82, 0
	v_mov_b32_e32 v83, 0
	v_mov_b32_e32 v84, 0
	v_mov_b32_e32 v85, 0
	v_mov_b32_e32 v86, 0
	v_mov_b32_e32 v87, 0
	v_mov_b32_e32 v88, 0
	v_mov_b32_e32 v89, 0
	v_mov_b32_e32 v90, 0
	v_mov_b32_e32 v91, 0
	v_mov_b32_e32 v92, 0
	v_mov_b32_e32 v93, 0
	v_mov_b32_e32 v94, 0
	v_mov_b32_e32 v95, 0
	v_mov_b32_e32 v64, 0
	v_mov_b32_e32 v65, 0
	v_mov_b32_e32 v66, 0
	v_mov_b32_e32 v67, 0
	v_mov_b32_e32 v68, 0
	v_mov_b32_e32 v69, 0
	v_mov_b32_e32 v70, 0
	v_mov_b32_e32 v71, 0
	v_mov_b32_e32 v72, 0
	v_mov_b32_e32 v73, 0
	v_mov_b32_e32 v74, 0
	v_mov_b32_e32 v75, 0
	v_mov_b32_e32 v76, 0
	v_mov_b32_e32 v77, 0
	v_mov_b32_e32 v78, 0
	v_mov_b32_e32 v79, 0
	v_mov_b32_e32 v48, 0
	v_mov_b32_e32 v49, 0
	v_mov_b32_e32 v50, 0
	v_mov_b32_e32 v51, 0
	v_mov_b32_e32 v52, 0
	v_mov_b32_e32 v53, 0
	v_mov_b32_e32 v54, 0
	v_mov_b32_e32 v55, 0
	v_mov_b32_e32 v56, 0
	v_mov_b32_e32 v57, 0
	v_mov_b32_e32 v58, 0
	v_mov_b32_e32 v59, 0
	v_mov_b32_e32 v60, 0
	v_mov_b32_e32 v61, 0
	v_mov_b32_e32 v62, 0
	v_mov_b32_e32 v63, 0
	v_mov_b32_e32 v32, 0
	v_mov_b32_e32 v33, 0
	v_mov_b32_e32 v34, 0
	v_mov_b32_e32 v35, 0
	v_mov_b32_e32 v36, 0
	v_mov_b32_e32 v37, 0
	v_mov_b32_e32 v38, 0
	v_mov_b32_e32 v39, 0
	v_mov_b32_e32 v40, 0
	v_mov_b32_e32 v41, 0
	v_mov_b32_e32 v42, 0
	v_mov_b32_e32 v43, 0
	v_mov_b32_e32 v44, 0
	v_mov_b32_e32 v45, 0
	v_mov_b32_e32 v46, 0
	v_mov_b32_e32 v47, 0
	v_mov_b32_e32 v16, 0
	v_mov_b32_e32 v17, 0
	v_mov_b32_e32 v18, 0
	v_mov_b32_e32 v19, 0
	v_mov_b32_e32 v20, 0
	v_mov_b32_e32 v21, 0
	v_mov_b32_e32 v22, 0
	v_mov_b32_e32 v23, 0
	v_mov_b32_e32 v24, 0
	v_mov_b32_e32 v25, 0
	v_mov_b32_e32 v26, 0
	v_mov_b32_e32 v27, 0
	v_mov_b32_e32 v28, 0
	v_mov_b32_e32 v29, 0
	v_mov_b32_e32 v30, 0
	v_mov_b32_e32 v31, 0
	v_mov_b32_e32 v0, 0
	v_mov_b32_e32 v1, 0
	v_mov_b32_e32 v2, 0
	v_mov_b32_e32 v3, 0
	v_mov_b32_e32 v4, 0
	v_mov_b32_e32 v5, 0
	v_mov_b32_e32 v6, 0
	v_mov_b32_e32 v7, 0
	v_mov_b32_e32 v8, 0
	v_mov_b32_e32 v9, 0
	v_mov_b32_e32 v10, 0
	v_mov_b32_e32 v11, 0
	v_mov_b32_e32 v12, 0
	v_mov_b32_e32 v13, 0
	v_mov_b32_e32 v14, 0
	v_mov_b32_e32 v15, 0
; #define MFMA32(a, b, c) __builtin_amdgcn_mfma_f32_32x32x16_bf16((a), (b), (c), 0, 0, 0)
; #define GA_LOAD(pr_) do { _Pragma("unroll") for (int i = 0; i < 4; ++i) ra[i] = *(const u32x4*)(Ab + (i * 32) * lda + (pr_) * 64); } while (0)
; #define GB_LOAD(kt_) do { const bfr* bk_ = Bb + (kt_) * NB * 32; \
;     _Pragma("unroll") for (int i = 0; i < 4; ++i) rb[i] = *(const u32x4*)(bk_ + (i * 64) * 32); } while (0)
; #define G_STORE(kt_) do { bfr* as_ = S0 + ((kt_) & 1) * GSTAGE; bfr* bs_ = as_ + 128 * 40; \
;     if (apar == ((kt_) & 1)) { _Pragma("unroll") for (int i = 0; i < 4; ++i) *(u32x4*)(as_ + asoff + i * 32 * 40) = ra[i]; } \
;     _Pragma("unroll") for (int i = 0; i < 4; ++i) *(u32x4*)(bs_ + bsoff + i * 64 * 40) = rb[i]; } while (0)
; template <int lda>
; DI void gemm_mainloop(const bfr* __restrict__ A, const bfr* __restrict__ Bt, int NB, int K, int m0, int n0, char* smem, f32x16 (&acc)[2][4]) {
;     ...
;   for (int kt = 0; kt < nk; ++kt) {
;     if (kt + 1 < nk) G_STORE(kt + 1);
;     if (kt + 2 < nk) {
;       GB_LOAD(kt + 2);
;       if ((kt & 1) == 0) GA_LOAD((kt >> 1) + 1);
;     }
;     const bfr* As = S0 + (kt & 1) * GSTAGE;
;     const bfr* Bs = As + 128 * 40;
; #pragma unroll
;     for (int ks = 0; ks < 2; ++ks) {
;       bf16x8 af[2], bfg[4];
; #pragma unroll
;       for (int i = 0; i < 2; ++i) af[i] = *(const bf16x8*)(As + (wr * 64 + i * 32 + r) * 40 + ks * 16 + hl * 8);
; #pragma unroll
;       for (int j = 0; j < 4; ++j) bfg[j] = *(const bf16x8*)(Bs + (wc * 128 + j * 32 + r) * 40 + ks * 16 + hl * 8);
; #pragma unroll
;       for (int i = 0; i < 2; ++i)
; #pragma unroll
;         for (int j = 0; j < 4; ++j) acc[i][j] = MFMA32(af[i], bfg[j], acc[i][j]);
;     }
;     __syncthreads();
;   }
.Lp8_loop:
	s_waitcnt vmcnt(6)
	s_barrier
	s_mul_i32 s74, s70, 0x6000
	s_add_u32 s75, s74, s68
	s_mov_b32 m0, s75
	s_add_u32 s76, s74, 0x2000
	s_cmp_eq_u32 s70, 2
	s_cselect_b32 s76, 0x10000, s76
	global_load_lds_dwordx4 v176, s[64:65]
	s_add_u32 m0, s75, 0x400
	s_add_u32 s76, s76, s69
	global_load_lds_dwordx4 v177, s[64:65]
	s_mov_b32 m0, s76
	s_add_u32 s64, s64, 64
	s_addc_u32 s65, s65, 0
	global_load_lds_dwordx4 v178, s[66:67]
	global_load_lds_dwordx4 v178, s[66:67] offset:1024
	global_load_lds_dwordx4 v178, s[66:67] offset:2048
	global_load_lds_dwordx4 v178, s[66:67] offset:3072
	s_add_u32 s66, s66, 0x10000
	s_addc_u32 s67, s67, 0
	s_add_u32 s70, s70, 1
	s_cmp_eq_u32 s70, 3
	s_cselect_b32 s70, 0, s70
	s_mul_i32 s74, s71, 0x6000
	s_add_u32 s75, s74, 0x2000
	s_cmp_eq_u32 s71, 2
	s_cselect_b32 s75, 0x10000, s75
	v_add_u32_e32 v183, s74, v179
	v_add_u32_e32 v185, s75, v181
	v_add_u32_e32 v184, s74, v180
	v_add_u32_e32 v186, s75, v182
	ds_read_b128 v[128:131], v183
	ds_read_b128 v[144:147], v185
	ds_read_b128 v[148:151], v185 offset:2048
	ds_read_b128 v[152:155], v185 offset:4096
	ds_read_b128 v[156:159], v185 offset:6144
	ds_read_b128 v[132:135], v183 offset:2048
	ds_read_b128 v[136:139], v184
	ds_read_b128 v[160:163], v186
	ds_read_b128 v[164:167], v186 offset:2048
	ds_read_b128 v[168:171], v186 offset:4096
	ds_read_b128 v[172:175], v186 offset:6144
	ds_read_b128 v[140:143], v184 offset:2048
	s_add_u32 s71, s71, 1
	s_cmp_eq_u32 s71, 3
	s_cselect_b32 s71, 0, s71
	s_waitcnt lgkmcnt(10)
	v_mfma_f32_32x32x16_bf16 v[112:127], v[128:131], v[144:147], v[112:127]
	s_waitcnt lgkmcnt(9)
	v_mfma_f32_32x32x16_bf16 v[96:111], v[128:131], v[148:151], v[96:111]
	s_waitcnt lgkmcnt(8)
	v_mfma_f32_32x32x16_bf16 v[80:95], v[128:131], v[152:155], v[80:95]
	s_waitcnt lgkmcnt(7)
	v_mfma_f32_32x32x16_bf16 v[64:79], v[128:131], v[156:159], v[64:79]
	s_waitcnt lgkmcnt(6)
	v_mfma_f32_32x32x16_bf16 v[48:63], v[132:135], v[144:147], v[48:63]
	v_mfma_f32_32x32x16_bf16 v[32:47], v[132:135], v[148:151], v[32:47]
	v_mfma_f32_32x32x16_bf16 v[16:31], v[132:135], v[152:155], v[16:31]
	v_mfma_f32_32x32x16_bf16 v[0:15], v[132:135], v[156:159], v[0:15]
	s_waitcnt lgkmcnt(4)
	v_mfma_f32_32x32x16_bf16 v[112:127], v[136:139], v[160:163], v[112:127]
	s_waitcnt lgkmcnt(3)
	v_mfma_f32_32x32x16_bf16 v[96:111], v[136:139], v[164:167], v[96:111]
	s_waitcnt lgkmcnt(2)
	v_mfma_f32_32x32x16_bf16 v[80:95], v[136:139], v[168:171], v[80:95]
	s_waitcnt lgkmcnt(1)
	v_mfma_f32_32x32x16_bf16 v[64:79], v[136:139], v[172:175], v[64:79]
	s_waitcnt lgkmcnt(0)
	v_mfma_f32_32x32x16_bf16 v[48:63], v[140:143], v[160:163], v[48:63]
	v_mfma_f32_32x32x16_bf16 v[32:47], v[140:143], v[164:167], v[32:47]
	v_mfma_f32_32x32x16_bf16 v[16:31], v[140:143], v[168:171], v[16:31]
	v_mfma_f32_32x32x16_bf16 v[0:15], v[140:143], v[172:175], v[0:15]
	s_add_u32 s72, s72, 1
	s_cmp_lt_u32 s72, 30
	s_cbranch_scc1 .Lp8_loop
	s_waitcnt vmcnt(6)
	s_barrier
; #define MFMA32(a, b, c) __builtin_amdgcn_mfma_f32_32x32x16_bf16((a), (b), (c), 0, 0, 0)
; #define GA_LOAD(pr_) do { _Pragma("unroll") for (int i = 0; i < 4; ++i) ra[i] = *(const u32x4*)(Ab + (i * 32) * lda + (pr_) * 64); } while (0)
; #define GB_LOAD(kt_) do { const bfr* bk_ = Bb + (kt_) * NB * 32; \
;     _Pragma("unroll") for (int i = 0; i < 4; ++i) rb[i] = *(const u32x4*)(bk_ + (i * 64) * 32); } while (0)
; #define G_STORE(kt_) do { bfr* as_ = S0 + ((kt_) & 1) * GSTAGE; bfr* bs_ = as_ + 128 * 40; \
;     if (apar == ((kt_) & 1)) { _Pragma("unroll") for (int i = 0; i < 4; ++i) *(u32x4*)(as_ + asoff + i * 32 * 40) = ra[i]; } \
;     _Pragma("unroll") for (int i = 0; i < 4; ++i) *(u32x4*)(bs_ + bsoff + i * 64 * 40) = rb[i]; } while (0)
; template <int lda>
; DI void gemm_mainloop(const bfr* __restrict__ A, const bfr* __restrict__ Bt, int NB, int K, int m0, int n0, char* smem, f32x16 (&acc)[2][4]) {
;     ...
;   for (int kt = 0; kt < nk; ++kt) {
;     if (kt + 1 < nk) G_STORE(kt + 1);
;     if (kt + 2 < nk) {
;       GB_LOAD(kt + 2);
;       if ((kt & 1) == 0) GA_LOAD((kt >> 1) + 1);
;     }
;     const bfr* As = S0 + (kt & 1) * GSTAGE;
;     const bfr* Bs = As + 128 * 40;
; #pragma unroll
;     for (int ks = 0; ks < 2; ++ks) {
;       bf16x8 af[2], bfg[4];
; #pragma unroll
;       for (int i = 0; i < 2; ++i) af[i] = *(const bf16x8*)(As + (wr * 64 + i * 32 + r) * 40 + ks * 16 + hl * 8);
; #pragma unroll
;       for (int j = 0; j < 4; ++j) bfg[j] = *(const bf16x8*)(Bs + (wc * 128 + j * 32 + r) * 40 + ks * 16 + hl * 8);
; #pragma unroll
;       for (int i = 0; i < 2; ++i)
; #pragma unroll
;         for (int j = 0; j < 4; ++j) acc[i][j] = MFMA32(af[i], bfg[j], acc[i][j]);
;     }
;     __syncthreads();
;   }
	s_mul_i32 s74, s71, 0x6000
	s_add_u32 s75, s74, 0x2000
	s_cmp_eq_u32 s71, 2
	s_cselect_b32 s75, 0x10000, s75
	v_add_u32_e32 v183, s74, v179
	v_add_u32_e32 v185, s75, v181
	v_add_u32_e32 v184, s74, v180
	v_add_u32_e32 v186, s75, v182
	ds_read_b128 v[128:131], v183
	ds_read_b128 v[144:147], v185
	ds_read_b128 v[148:151], v185 offset:2048
	ds_read_b128 v[152:155], v185 offset:4096
	ds_read_b128 v[156:159], v185 offset:6144
	ds_read_b128 v[132:135], v183 offset:2048
	ds_read_b128 v[136:139], v184
	ds_read_b128 v[160:163], v186
	ds_read_b128 v[164:167], v186 offset:2048
	ds_read_b128 v[168:171], v186 offset:4096
	ds_read_b128 v[172:175], v186 offset:6144
	ds_read_b128 v[140:143], v184 offset:2048
	s_add_u32 s71, s71, 1
	s_cmp_eq_u32 s71, 3
	s_cselect_b32 s71, 0, s71
	s_waitcnt lgkmcnt(10)
	v_mfma_f32_32x32x16_bf16 v[112:127], v[128:131], v[144:147], v[112:127]
	s_waitcnt lgkmcnt(9)
	v_mfma_f32_32x32x16_bf16 v[96:111], v[128:131], v[148:151], v[96:111]
	s_waitcnt lgkmcnt(8)
	v_mfma_f32_32x32x16_bf16 v[80:95], v[128:131], v[152:155], v[80:95]
	s_waitcnt lgkmcnt(7)
	v_mfma_f32_32x32x16_bf16 v[64:79], v[128:131], v[156:159], v[64:79]
	s_waitcnt lgkmcnt(6)
	v_mfma_f32_32x32x16_bf16 v[48:63], v[132:135], v[144:147], v[48:63]
	v_mfma_f32_32x32x16_bf16 v[32:47], v[132:135], v[148:151], v[32:47]
	v_mfma_f32_32x32x16_bf16 v[16:31], v[132:135], v[152:155], v[16:31]
	v_mfma_f32_32x32x16_bf16 v[0:15], v[132:135], v[156:159], v[0:15]
	s_waitcnt lgkmcnt(4)
	v_mfma_f32_32x32x16_bf16 v[112:127], v[136:139], v[160:163], v[112:127]
	s_waitcnt lgkmcnt(3)
	v_mfma_f32_32x32x16_bf16 v[96:111], v[136:139], v[164:167], v[96:111]
	s_waitcnt lgkmcnt(2)
	v_mfma_f32_32x32x16_bf16 v[80:95], v[136:139], v[168:171], v[80:95]
	s_waitcnt lgkmcnt(1)
	v_mfma_f32_32x32x16_bf16 v[64:79], v[136:139], v[172:175], v[64:79]
	s_waitcnt lgkmcnt(0)
	v_mfma_f32_32x32x16_bf16 v[48:63], v[140:143], v[160:163], v[48:63]
	v_mfma_f32_32x32x16_bf16 v[32:47], v[140:143], v[164:167], v[32:47]
	v_mfma_f32_32x32x16_bf16 v[16:31], v[140:143], v[168:171], v[16:31]
	v_mfma_f32_32x32x16_bf16 v[0:15], v[140:143], v[172:175], v[0:15]
	s_waitcnt vmcnt(0)
	s_barrier
	s_mul_i32 s74, s71, 0x6000
	s_add_u32 s75, s74, 0x2000
	s_cmp_eq_u32 s71, 2
	s_cselect_b32 s75, 0x10000, s75
	v_add_u32_e32 v183, s74, v179
	v_add_u32_e32 v185, s75, v181
	v_add_u32_e32 v184, s74, v180
	v_add_u32_e32 v186, s75, v182
	ds_read_b128 v[128:131], v183
	ds_read_b128 v[144:147], v185
	ds_read_b128 v[148:151], v185 offset:2048
	ds_read_b128 v[152:155], v185 offset:4096
	ds_read_b128 v[156:159], v185 offset:6144
	ds_read_b128 v[132:135], v183 offset:2048
	ds_read_b128 v[136:139], v184
	ds_read_b128 v[160:163], v186
	ds_read_b128 v[164:167], v186 offset:2048
	ds_read_b128 v[168:171], v186 offset:4096
	ds_read_b128 v[172:175], v186 offset:6144
	ds_read_b128 v[140:143], v184 offset:2048
	s_add_u32 s71, s71, 1
	s_cmp_eq_u32 s71, 3
	s_cselect_b32 s71, 0, s71
	s_waitcnt lgkmcnt(10)
	v_mfma_f32_32x32x16_bf16 v[112:127], v[128:131], v[144:147], v[112:127]
	s_waitcnt lgkmcnt(9)
	v_mfma_f32_32x32x16_bf16 v[96:111], v[128:131], v[148:151], v[96:111]
	s_waitcnt lgkmcnt(8)
	v_mfma_f32_32x32x16_bf16 v[80:95], v[128:131], v[152:155], v[80:95]
	s_waitcnt lgkmcnt(7)
	v_mfma_f32_32x32x16_bf16 v[64:79], v[128:131], v[156:159], v[64:79]
	s_waitcnt lgkmcnt(6)
	v_mfma_f32_32x32x16_bf16 v[48:63], v[132:135], v[144:147], v[48:63]
	v_mfma_f32_32x32x16_bf16 v[32:47], v[132:135], v[148:151], v[32:47]
	v_mfma_f32_32x32x16_bf16 v[16:31], v[132:135], v[152:155], v[16:31]
	v_mfma_f32_32x32x16_bf16 v[0:15], v[132:135], v[156:159], v[0:15]
	s_waitcnt lgkmcnt(4)
	v_mfma_f32_32x32x16_bf16 v[112:127], v[136:139], v[160:163], v[112:127]
	s_waitcnt lgkmcnt(3)
	v_mfma_f32_32x32x16_bf16 v[96:111], v[136:139], v[164:167], v[96:111]
	s_waitcnt lgkmcnt(2)
	v_mfma_f32_32x32x16_bf16 v[80:95], v[136:139], v[168:171], v[80:95]
	s_waitcnt lgkmcnt(1)
	v_mfma_f32_32x32x16_bf16 v[64:79], v[136:139], v[172:175], v[64:79]
	s_waitcnt lgkmcnt(0)
	v_mfma_f32_32x32x16_bf16 v[48:63], v[140:143], v[160:163], v[48:63]
	v_mfma_f32_32x32x16_bf16 v[32:47], v[140:143], v[164:167], v[32:47]
	v_mfma_f32_32x32x16_bf16 v[16:31], v[140:143], v[168:171], v[16:31]
	v_mfma_f32_32x32x16_bf16 v[0:15], v[140:143], v[172:175], v[0:15]
	s_nop 7
	v_readlane_b32 s64, v187, 0
	v_readlane_b32 s65, v187, 1
	v_readlane_b32 s66, v187, 2
	v_readlane_b32 s67, v187, 3
	v_readlane_b32 s68, v187, 4
	v_readlane_b32 s69, v187, 5
	v_readlane_b32 s70, v187, 6
	v_readlane_b32 s71, v187, 7
	v_readlane_b32 s72, v187, 8
	v_readlane_b32 s73, v187, 9
	v_readlane_b32 s74, v187, 10
	v_readlane_b32 s75, v187, 11
	v_readlane_b32 s76, v187, 12
	v_readlane_b32 s77, v187, 13
	v_readlane_b32 s78, v187, 14
	v_readlane_b32 s79, v187, 15
	s_nop 7
	s_branch .LBB0_922

; __global__ void __launch_bounds__(256, 2) mega(Params p) {
;   __shared__ __attribute__((aligned(16))) char smem[65536];
	.amdhsa_kernel _Z4mega6Params
		.amdhsa_group_segment_fixed_size 81920
		.amdhsa_private_segment_fixed_size 0
		.amdhsa_kernarg_size 768
		.amdhsa_user_sgpr_count 2
		.amdhsa_user_sgpr_dispatch_ptr 0
		.amdhsa_user_sgpr_queue_ptr 0
		.amdhsa_user_sgpr_kernarg_segment_ptr 1
		.amdhsa_user_sgpr_dispatch_id 0
		.amdhsa_user_sgpr_kernarg_preload_length 0
		.amdhsa_user_sgpr_kernarg_preload_offset 0
		.amdhsa_user_sgpr_private_segment_size 0
		.amdhsa_uses_dynamic_stack 0
		.amdhsa_enable_private_segment 0
		.amdhsa_system_sgpr_workgroup_id_x 1
		.amdhsa_system_sgpr_workgroup_id_y 0
		.amdhsa_system_sgpr_workgroup_id_z 0
		.amdhsa_system_sgpr_workgroup_info 0
		.amdhsa_system_vgpr_workitem_id 2
		.amdhsa_next_free_vgpr 255
		.amdhsa_next_free_sgpr 102
		.amdhsa_accum_offset 256
		.amdhsa_reserve_vcc 1
		.amdhsa_float_round_mode_32 0
		.amdhsa_float_round_mode_16_64 0
		.amdhsa_float_denorm_mode_32 3
		.amdhsa_float_denorm_mode_16_64 3
		.amdhsa_dx10_clamp 1
		.amdhsa_ieee_mode 1
		.amdhsa_fp16_overflow 0
		.amdhsa_tg_split 0
		.amdhsa_exception_fp_ieee_invalid_op 0
		.amdhsa_exception_fp_denorm_src 0
		.amdhsa_exception_fp_ieee_div_zero 0
		.amdhsa_exception_fp_ieee_overflow 0
		.amdhsa_exception_fp_ieee_underflow 0
		.amdhsa_exception_fp_ieee_inexact 0
		.amdhsa_exception_int_div_zero 0
	.end_amdhsa_kernel

; __global__ void __launch_bounds__(256, 2) mega(Params p) {
;   __shared__ __attribute__((aligned(16))) char smem[65536];
amdhsa.kernels:
  - .agpr_count:     0
    .args:
      - .offset:         0
        .size:           512
        .value_kind:     by_value
      - .offset:         512
        .size:           4
        .value_kind:     hidden_block_count_x
      - .offset:         516
        .size:           4
        .value_kind:     hidden_block_count_y
      - .offset:         520
        .size:           4
        .value_kind:     hidden_block_count_z
      - .offset:         524
        .size:           2
        .value_kind:     hidden_group_size_x
      - .offset:         526
        .size:           2
        .value_kind:     hidden_group_size_y
      - .offset:         528
        .size:           2
        .value_kind:     hidden_group_size_z
      - .offset:         530
        .size:           2
        .value_kind:     hidden_remainder_x
      - .offset:         532
        .size:           2
        .value_kind:     hidden_remainder_y
      - .offset:         534
        .size:           2
        .value_kind:     hidden_remainder_z
      - .offset:         552
        .size:           8
        .value_kind:     hidden_global_offset_x
      - .offset:         560
        .size:           8
        .value_kind:     hidden_global_offset_y
      - .offset:         568
        .size:           8
        .value_kind:     hidden_global_offset_z
      - .offset:         576
        .size:           2
        .value_kind:     hidden_grid_dims
      - .offset:         600
        .size:           8
        .value_kind:     hidden_multigrid_sync_arg
    .group_segment_fixed_size: 81920
    .kernarg_segment_align: 8
    .kernarg_segment_size: 768
    .language:       OpenCL C
    .language_version:
      - 2
      - 0
    .max_flat_workgroup_size: 256
    .name:           _Z4mega6Params
    .private_segment_fixed_size: 0
    .sgpr_count:     108
    .sgpr_spill_count: 69
    .symbol:         _Z4mega6Params.kd
    .uniform_work_group_size: 1
    .uses_dynamic_stack: false
    .vgpr_count:     255
    .vgpr_spill_count: 0
    .wavefront_size: 64
